# v18 + HGRN chunk loop (the even mixer's critical serial chain) runs at wave priority 2/3 instead of 0/1 so it wins issue slots over co-resident attention/conversion work
# speedup vs baseline: 1.0049x; 1.0027x over previous
.LBB0_783:
	s_sub_i32 s24, s48, 64
	s_lshr_b32 s29, s24, 3
	s_and_b64 s[24:25], exec, s[0:1]
	s_movk_i32 s24, 0x400
	s_cselect_b32 s27, s24, 0x100
	s_cselect_b32 s24, s28, s29
	s_lshl_b32 s24, s24, 10
	s_addk_i32 s24, 0x2000
	s_lshl_b32 s25, s29, 8
	s_and_b64 s[0:1], exec, s[0:1]
	s_cselect_b32 s97, s24, s25
	s_lshr_b32 s30, s27, 5
	s_cmp_eq_u32 s2, 0
	s_cselect_b64 vcc, -1, 0
	s_and_b64 s[0:1], vcc, exec
	s_mov_b32 s0, 0xc4fd000
	s_cselect_b32 s0, s0, 0xe4fd000
	s_add_u32 s0, s94, s0
	s_addc_u32 s1, s95, 0
	s_lshl_b32 s24, s21, 9
	s_add_u32 s36, s0, s24
	s_addc_u32 s37, s1, 0
	s_lshl_b32 s0, s21, 8
	v_readlane_b32 s1, v234, 14
	s_add_u32 s28, s1, s0
	v_readlane_b32 s1, v234, 15
	v_writelane_b32 v232, s29, 57
	s_addc_u32 s29, s1, 0
	v_readlane_b32 s1, v234, 16
	s_add_u32 s0, s1, s0
	v_readlane_b32 s1, v234, 17
	s_addc_u32 s1, s1, 0
	s_lshl_b32 s25, s2, 25
	v_readlane_b32 s38, v235, 44
	s_add_u32 s25, s38, s25
	v_readlane_b32 s38, v235, 45
	s_addc_u32 s38, s38, 0
	s_add_u32 s40, s25, s24
	v_lshlrev_b32_e32 v32, 4, v81
	s_addc_u32 s41, s38, 0
	v_xad_u32 v34, v32, -1, s27
	s_and_b64 s[24:25], vcc, exec
	v_cndmask_b32_e32 v34, v34, v32, vcc
	s_cselect_b32 s24, 1, -1
	v_add_u32_e32 v34, s97, v34
	v_or_b32_e32 v42, v80, v133
	v_add_u32_e32 v36, s24, v34
	v_ashrrev_i32_e32 v35, 31, v34
	v_ashrrev_i32_e32 v43, 31, v42
	v_lshlrev_b64 v[34:35], 9, v[34:35]
	v_ashrrev_i32_e32 v37, 31, v36
	v_lshl_add_u64 v[34:35], v[34:35], 0, v[42:43]
	v_lshlrev_b64 v[36:37], 9, v[36:37]
	v_lshl_add_u64 v[38:39], v[34:35], 2, s[36:37]
	v_lshl_add_u64 v[36:37], v[36:37], 0, v[42:43]
	v_mov_b32_e32 v226, s24
	v_lshl_add_u64 v[222:223], v[34:35], 1, s[28:29]
	v_lshlrev_b32_e32 v226, 11, v226
	v_lshl_add_u64 v[224:225], v[34:35], 1, s[0:1]
	v_ashrrev_i32_e32 v227, 31, v226
	v_lshl_add_u64 v[220:221], v[34:35], 2, s[36:37]
	v_ashrrev_i32_e32 v228, 1, v226
	v_mov_b32_e32 v229, v227
	global_load_dword v236, v[220:221], off
	global_load_ushort v237, v[222:223], off
	global_load_ushort v238, v[224:225], off
	v_lshl_add_u64 v[220:221], v[220:221], 0, v[226:227]
	v_lshl_add_u64 v[222:223], v[222:223], 0, v[228:229]
	v_lshl_add_u64 v[224:225], v[224:225], 0, v[228:229]
	global_load_dword v239, v[220:221], off
	global_load_ushort v240, v[222:223], off
	global_load_ushort v241, v[224:225], off
	v_lshl_add_u64 v[220:221], v[220:221], 0, v[226:227]
	v_lshl_add_u64 v[222:223], v[222:223], 0, v[228:229]
	v_lshl_add_u64 v[224:225], v[224:225], 0, v[228:229]
	global_load_dword v242, v[220:221], off
	global_load_ushort v243, v[222:223], off
	global_load_ushort v244, v[224:225], off
	v_lshl_add_u64 v[220:221], v[220:221], 0, v[226:227]
	v_lshl_add_u64 v[222:223], v[222:223], 0, v[228:229]
	v_lshl_add_u64 v[224:225], v[224:225], 0, v[228:229]
	global_load_dword v245, v[220:221], off
	global_load_ushort v246, v[222:223], off
	global_load_ushort v247, v[224:225], off
	v_lshl_add_u64 v[220:221], v[220:221], 0, v[226:227]
	v_lshl_add_u64 v[222:223], v[222:223], 0, v[228:229]
	v_lshl_add_u64 v[224:225], v[224:225], 0, v[228:229]
	global_load_dword v248, v[220:221], off
	global_load_ushort v249, v[222:223], off
	global_load_ushort v250, v[224:225], off
	v_lshl_add_u64 v[220:221], v[220:221], 0, v[226:227]
	v_lshl_add_u64 v[222:223], v[222:223], 0, v[228:229]
	v_lshl_add_u64 v[224:225], v[224:225], 0, v[228:229]
	global_load_dword v251, v[220:221], off
	global_load_ushort v236, v[222:223], off
	global_load_ushort v237, v[224:225], off
	v_lshl_add_u64 v[220:221], v[220:221], 0, v[226:227]
	v_lshl_add_u64 v[222:223], v[222:223], 0, v[228:229]
	v_lshl_add_u64 v[224:225], v[224:225], 0, v[228:229]
	global_load_dword v238, v[220:221], off
	global_load_ushort v239, v[222:223], off
	global_load_ushort v240, v[224:225], off
	v_lshl_add_u64 v[220:221], v[220:221], 0, v[226:227]
	v_lshl_add_u64 v[222:223], v[222:223], 0, v[228:229]
	v_lshl_add_u64 v[224:225], v[224:225], 0, v[228:229]
	global_load_dword v241, v[220:221], off
	global_load_ushort v242, v[222:223], off
	global_load_ushort v243, v[224:225], off
	v_lshl_add_u64 v[220:221], v[220:221], 0, v[226:227]
	v_lshl_add_u64 v[222:223], v[222:223], 0, v[228:229]
	v_lshl_add_u64 v[224:225], v[224:225], 0, v[228:229]
	global_load_dword v244, v[220:221], off
	global_load_ushort v245, v[222:223], off
	global_load_ushort v246, v[224:225], off
	v_lshl_add_u64 v[220:221], v[220:221], 0, v[226:227]
	v_lshl_add_u64 v[222:223], v[222:223], 0, v[228:229]
	v_lshl_add_u64 v[224:225], v[224:225], 0, v[228:229]
	global_load_dword v247, v[220:221], off
	global_load_ushort v248, v[222:223], off
	global_load_ushort v249, v[224:225], off
	v_lshl_add_u64 v[220:221], v[220:221], 0, v[226:227]
	v_lshl_add_u64 v[222:223], v[222:223], 0, v[228:229]
	v_lshl_add_u64 v[224:225], v[224:225], 0, v[228:229]
	global_load_dword v250, v[220:221], off
	global_load_ushort v251, v[222:223], off
	global_load_ushort v236, v[224:225], off
	v_lshl_add_u64 v[220:221], v[220:221], 0, v[226:227]
	v_lshl_add_u64 v[222:223], v[222:223], 0, v[228:229]
	v_lshl_add_u64 v[224:225], v[224:225], 0, v[228:229]
	global_load_dword v237, v[220:221], off
	global_load_ushort v238, v[222:223], off
	global_load_ushort v239, v[224:225], off
	v_lshl_add_u64 v[220:221], v[220:221], 0, v[226:227]
	v_lshl_add_u64 v[222:223], v[222:223], 0, v[228:229]
	v_lshl_add_u64 v[224:225], v[224:225], 0, v[228:229]
	global_load_dword v240, v[220:221], off
	global_load_ushort v241, v[222:223], off
	global_load_ushort v242, v[224:225], off
	v_lshl_add_u64 v[220:221], v[220:221], 0, v[226:227]
	v_lshl_add_u64 v[222:223], v[222:223], 0, v[228:229]
	v_lshl_add_u64 v[224:225], v[224:225], 0, v[228:229]
	global_load_dword v243, v[220:221], off
	global_load_ushort v244, v[222:223], off
	global_load_ushort v245, v[224:225], off
	v_lshl_add_u64 v[220:221], v[220:221], 0, v[226:227]
	v_lshl_add_u64 v[222:223], v[222:223], 0, v[228:229]
	v_lshl_add_u64 v[224:225], v[224:225], 0, v[228:229]
	global_load_dword v246, v[220:221], off
	global_load_ushort v247, v[222:223], off
	global_load_ushort v248, v[224:225], off
	v_lshl_add_u64 v[220:221], v[220:221], 0, v[226:227]
	v_lshl_add_u64 v[222:223], v[222:223], 0, v[228:229]
	v_lshl_add_u64 v[224:225], v[224:225], 0, v[228:229]
	global_load_dword v249, v[220:221], off
	global_load_ushort v250, v[222:223], off
	global_load_ushort v251, v[224:225], off
	global_load_dword v44, v[38:39], off
	v_lshl_add_u64 v[38:39], v[36:37], 2, s[36:37]
	v_lshlrev_b64 v[34:35], 1, v[34:35]
	global_load_dword v45, v[38:39], off
	v_lshl_add_u64 v[38:39], s[28:29], 0, v[34:35]
	v_lshlrev_b64 v[36:37], 1, v[36:37]
	global_load_ushort v40, v[38:39], off
	v_lshl_add_u64 v[38:39], s[28:29], 0, v[36:37]
	global_load_ushort v38, v[38:39], off
	v_lshl_add_u64 v[34:35], s[0:1], 0, v[34:35]
	v_or_b32_e32 v80, 2, v32
	s_movk_i32 s25, 0x50
	v_lshlrev_b32_e32 v136, 3, v81
	v_cmp_eq_u32_e64 s[38:39], 0, v81
	s_mov_b32 s31, 0
	v_xad_u32 v148, v133, -1, s27
	v_writelane_b32 v232, s21, 58
	s_waitcnt vmcnt(0)
	v_lshl_or_b32 v113, v38, 16, v40
	global_load_ushort v38, v[34:35], off
	v_lshl_add_u64 v[34:35], s[0:1], 0, v[36:37]
	global_load_ushort v34, v[34:35], off
	v_xad_u32 v35, v32, -3, s27
	v_cndmask_b32_e32 v35, v35, v80, vcc
	v_add_u32_e32 v36, s97, v35
	v_ashrrev_i32_e32 v37, 31, v36
	v_mul_u32_u24_e32 v80, 0x88, v80
	v_add_lshl_u32 v141, v42, v80, 1
	v_add_u32_e32 v142, 0x220, v141
	v_add_u32_e32 v143, 0x440, v141
	v_add_u32_e32 v144, 0x660, v141
	v_add_u32_e32 v145, 0x880, v141
	v_add_u32_e32 v146, 0xaa0, v141
	v_add_u32_e32 v147, 0xcc0, v141
	s_waitcnt vmcnt(0)
	v_lshl_or_b32 v34, v34, 16, v38
	v_add_u32_e32 v38, s24, v36
	v_lshlrev_b64 v[36:37], 9, v[36:37]
	v_ashrrev_i32_e32 v39, 31, v38
	v_lshl_add_u64 v[36:37], v[36:37], 0, v[42:43]
	v_lshlrev_b64 v[38:39], 9, v[38:39]
	v_lshl_add_u64 v[40:41], v[36:37], 2, s[36:37]
	v_lshl_add_u64 v[38:39], v[38:39], 0, v[42:43]
	global_load_dword v46, v[40:41], off
	v_lshl_add_u64 v[40:41], v[38:39], 2, s[36:37]
	v_lshlrev_b64 v[36:37], 1, v[36:37]
	global_load_dword v47, v[40:41], off
	v_lshl_add_u64 v[40:41], s[28:29], 0, v[36:37]
	v_lshlrev_b64 v[38:39], 1, v[38:39]
	global_load_ushort v35, v[40:41], off
	v_lshl_add_u64 v[40:41], s[28:29], 0, v[38:39]
	global_load_ushort v40, v[40:41], off
	v_lshl_add_u64 v[36:37], s[0:1], 0, v[36:37]
	s_waitcnt vmcnt(0)
	v_lshl_or_b32 v115, v40, 16, v35
	global_load_ushort v35, v[36:37], off
	v_lshl_add_u64 v[36:37], s[0:1], 0, v[38:39]
	global_load_ushort v36, v[36:37], off
	v_xad_u32 v37, v32, -5, s27
	s_waitcnt vmcnt(0)
	v_lshl_or_b32 v35, v36, 16, v35
	v_or_b32_e32 v36, 4, v32
	v_cndmask_b32_e32 v36, v37, v36, vcc
	v_add_u32_e32 v36, s97, v36
	v_add_u32_e32 v38, s24, v36
	v_ashrrev_i32_e32 v37, 31, v36
	v_lshlrev_b64 v[36:37], 9, v[36:37]
	v_ashrrev_i32_e32 v39, 31, v38
	v_lshl_add_u64 v[36:37], v[36:37], 0, v[42:43]
	v_lshlrev_b64 v[38:39], 9, v[38:39]
	v_lshl_add_u64 v[40:41], v[36:37], 2, s[36:37]
	v_lshl_add_u64 v[38:39], v[38:39], 0, v[42:43]
	global_load_dword v118, v[40:41], off
	v_lshl_add_u64 v[40:41], v[38:39], 2, s[36:37]
	v_lshlrev_b64 v[36:37], 1, v[36:37]
	global_load_dword v119, v[40:41], off
	v_lshl_add_u64 v[40:41], s[28:29], 0, v[36:37]
	v_lshlrev_b64 v[38:39], 1, v[38:39]
	global_load_ushort v82, v[40:41], off
	v_lshl_add_u64 v[40:41], s[28:29], 0, v[38:39]
	global_load_ushort v40, v[40:41], off
	v_lshl_add_u64 v[36:37], s[0:1], 0, v[36:37]
	s_waitcnt vmcnt(0)
	v_lshl_or_b32 v134, v40, 16, v82
	global_load_ushort v40, v[36:37], off
	v_lshl_add_u64 v[36:37], s[0:1], 0, v[38:39]
	global_load_ushort v36, v[36:37], off
	v_or_b32_e32 v37, 6, v32
	v_xad_u32 v38, v32, -7, s27
	v_cndmask_b32_e32 v37, v38, v37, vcc
	v_add_u32_e32 v38, s97, v37
	v_ashrrev_i32_e32 v39, 31, v38
	s_waitcnt vmcnt(0)
	v_lshl_or_b32 v36, v36, 16, v40
	v_add_u32_e32 v40, s24, v38
	v_lshlrev_b64 v[38:39], 9, v[38:39]
	v_ashrrev_i32_e32 v41, 31, v40
	v_lshl_add_u64 v[38:39], v[38:39], 0, v[42:43]
	v_lshlrev_b64 v[40:41], 9, v[40:41]
	v_lshl_add_u64 v[82:83], v[38:39], 2, s[36:37]
	v_lshl_add_u64 v[40:41], v[40:41], 0, v[42:43]
	global_load_dword v120, v[82:83], off
	v_lshl_add_u64 v[82:83], v[40:41], 2, s[36:37]
	v_lshlrev_b64 v[38:39], 1, v[38:39]
	global_load_dword v121, v[82:83], off
	v_lshl_add_u64 v[82:83], s[28:29], 0, v[38:39]
	v_lshlrev_b64 v[40:41], 1, v[40:41]
	global_load_ushort v37, v[82:83], off
	v_lshl_add_u64 v[82:83], s[28:29], 0, v[40:41]
	global_load_ushort v82, v[82:83], off
	v_lshl_add_u64 v[38:39], s[0:1], 0, v[38:39]
	s_waitcnt vmcnt(0)
	v_lshl_or_b32 v140, v82, 16, v37
	global_load_ushort v37, v[38:39], off
	v_lshl_add_u64 v[38:39], s[0:1], 0, v[40:41]
	global_load_ushort v38, v[38:39], off
	v_xad_u32 v39, v32, -9, s27
	s_waitcnt vmcnt(0)
	v_lshl_or_b32 v37, v38, 16, v37
	v_or_b32_e32 v38, 8, v32
	v_cndmask_b32_e32 v38, v39, v38, vcc
	v_add_u32_e32 v38, s97, v38
	v_add_u32_e32 v40, s24, v38
	v_ashrrev_i32_e32 v39, 31, v38
	v_lshlrev_b64 v[38:39], 9, v[38:39]
	v_ashrrev_i32_e32 v41, 31, v40
	v_lshl_add_u64 v[38:39], v[38:39], 0, v[42:43]
	v_lshlrev_b64 v[40:41], 9, v[40:41]
	v_lshl_add_u64 v[82:83], v[38:39], 2, s[36:37]
	v_lshl_add_u64 v[40:41], v[40:41], 0, v[42:43]
	global_load_dword v122, v[82:83], off
	v_lshl_add_u64 v[82:83], v[40:41], 2, s[36:37]
	v_lshlrev_b64 v[38:39], 1, v[38:39]
	global_load_dword v123, v[82:83], off
	v_lshl_add_u64 v[82:83], s[28:29], 0, v[38:39]
	v_lshlrev_b64 v[40:41], 1, v[40:41]
	global_load_ushort v84, v[82:83], off
	v_lshl_add_u64 v[82:83], s[28:29], 0, v[40:41]
	global_load_ushort v82, v[82:83], off
	v_lshl_add_u64 v[38:39], s[0:1], 0, v[38:39]
	s_waitcnt vmcnt(0)
	v_lshl_or_b32 v152, v82, 16, v84
	global_load_ushort v82, v[38:39], off
	v_lshl_add_u64 v[38:39], s[0:1], 0, v[40:41]
	global_load_ushort v38, v[38:39], off
	v_or_b32_e32 v39, 10, v32
	v_xad_u32 v40, v32, -11, s27
	v_cndmask_b32_e32 v39, v40, v39, vcc
	v_add_u32_e32 v40, s97, v39
	v_ashrrev_i32_e32 v41, 31, v40
	s_waitcnt vmcnt(0)
	v_lshl_or_b32 v38, v38, 16, v82
	v_add_u32_e32 v82, s24, v40
	v_lshlrev_b64 v[40:41], 9, v[40:41]
	v_ashrrev_i32_e32 v83, 31, v82
	v_lshl_add_u64 v[40:41], v[40:41], 0, v[42:43]
	v_lshlrev_b64 v[82:83], 9, v[82:83]
	v_lshl_add_u64 v[84:85], v[40:41], 2, s[36:37]
	v_lshl_add_u64 v[82:83], v[82:83], 0, v[42:43]
	global_load_dword v124, v[84:85], off
	v_lshl_add_u64 v[84:85], v[82:83], 2, s[36:37]
	v_lshlrev_b64 v[40:41], 1, v[40:41]
	global_load_dword v125, v[84:85], off
	v_lshl_add_u64 v[84:85], s[28:29], 0, v[40:41]
	v_lshlrev_b64 v[82:83], 1, v[82:83]
	global_load_ushort v39, v[84:85], off
	v_lshl_add_u64 v[84:85], s[28:29], 0, v[82:83]
	global_load_ushort v84, v[84:85], off
	v_lshl_add_u64 v[40:41], s[0:1], 0, v[40:41]
	s_waitcnt vmcnt(0)
	v_lshl_or_b32 v153, v84, 16, v39
	global_load_ushort v39, v[40:41], off
	v_lshl_add_u64 v[40:41], s[0:1], 0, v[82:83]
	global_load_ushort v40, v[40:41], off
	v_xad_u32 v41, v32, -13, s27
	s_waitcnt vmcnt(0)
	v_lshl_or_b32 v39, v40, 16, v39
	v_or_b32_e32 v40, 12, v32
	v_cndmask_b32_e32 v40, v41, v40, vcc
	v_add_u32_e32 v40, s97, v40
	v_add_u32_e32 v82, s24, v40
	v_ashrrev_i32_e32 v41, 31, v40
	v_lshlrev_b64 v[40:41], 9, v[40:41]
	v_ashrrev_i32_e32 v83, 31, v82
	v_lshl_add_u64 v[40:41], v[40:41], 0, v[42:43]
	v_lshlrev_b64 v[82:83], 9, v[82:83]
	v_lshl_add_u64 v[84:85], v[40:41], 2, s[36:37]
	v_lshl_add_u64 v[82:83], v[82:83], 0, v[42:43]
	global_load_dword v128, v[84:85], off
	v_lshl_add_u64 v[84:85], v[82:83], 2, s[36:37]
	v_lshlrev_b64 v[40:41], 1, v[40:41]
	global_load_dword v129, v[84:85], off
	v_lshl_add_u64 v[84:85], s[28:29], 0, v[40:41]
	v_lshlrev_b64 v[82:83], 1, v[82:83]
	global_load_ushort v86, v[84:85], off
	v_lshl_add_u64 v[84:85], s[28:29], 0, v[82:83]
	global_load_ushort v84, v[84:85], off
	v_lshl_add_u64 v[40:41], s[0:1], 0, v[40:41]
	s_waitcnt vmcnt(0)
	v_lshl_or_b32 v154, v84, 16, v86
	global_load_ushort v84, v[40:41], off
	v_lshl_add_u64 v[40:41], s[0:1], 0, v[82:83]
	global_load_ushort v40, v[40:41], off
	v_or_b32_e32 v41, 14, v32
	v_xad_u32 v82, v32, -15, s27
	v_cndmask_b32_e32 v41, v82, v41, vcc
	v_add_u32_e32 v82, s97, v41
	v_ashrrev_i32_e32 v83, 31, v82
	s_waitcnt vmcnt(0)
	v_lshl_or_b32 v40, v40, 16, v84
	v_add_u32_e32 v84, s24, v82
	v_lshlrev_b64 v[82:83], 9, v[82:83]
	v_ashrrev_i32_e32 v85, 31, v84
	v_lshl_add_u64 v[82:83], v[82:83], 0, v[42:43]
	v_lshlrev_b64 v[84:85], 9, v[84:85]
	v_lshl_add_u64 v[86:87], v[82:83], 2, s[36:37]
	v_lshl_add_u64 v[84:85], v[84:85], 0, v[42:43]
	global_load_dword v130, v[86:87], off
	v_lshl_add_u64 v[86:87], v[84:85], 2, s[36:37]
	v_lshlrev_b64 v[82:83], 1, v[82:83]
	global_load_dword v131, v[86:87], off
	v_lshl_add_u64 v[86:87], s[28:29], 0, v[82:83]
	v_lshlrev_b64 v[84:85], 1, v[84:85]
	global_load_ushort v41, v[86:87], off
	v_lshl_add_u64 v[86:87], s[28:29], 0, v[84:85]
	global_load_ushort v86, v[86:87], off
	v_lshl_add_u64 v[82:83], s[0:1], 0, v[82:83]
	s_waitcnt vmcnt(0)
	v_lshl_or_b32 v155, v86, 16, v41
	global_load_ushort v41, v[82:83], off
	v_lshl_add_u64 v[82:83], s[0:1], 0, v[84:85]
	global_load_ushort v82, v[82:83], off
	v_lshlrev_b32_e32 v85, 2, v81
	v_or_b32_e32 v80, 2, v85
	v_cmp_gt_u32_e64 s[44:45], v80, v133
	v_or_b32_e32 v80, 3, v85
	v_cmp_gt_u32_e64 s[46:47], v80, v133
	v_or_b32_e32 v80, 8, v85
	v_cmp_gt_u32_e64 s[48:49], v80, v133
	v_or_b32_e32 v80, 9, v85
	v_cmp_gt_u32_e64 s[50:51], v80, v133
	v_or_b32_e32 v80, 10, v85
	v_cmp_gt_u32_e64 s[52:53], v80, v133
	v_or_b32_e32 v80, 11, v85
	v_cmp_gt_u32_e64 s[54:55], v80, v133
	v_or_b32_e32 v80, 16, v85
	v_cmp_gt_u32_e64 s[56:57], v80, v133
	v_or_b32_e32 v80, 17, v85
	v_cmp_gt_u32_e64 s[58:59], v80, v133
	v_or_b32_e32 v80, 18, v85
	v_cmp_gt_u32_e64 s[60:61], v80, v133
	v_or_b32_e32 v80, 19, v85
	v_cmp_gt_u32_e64 s[62:63], v80, v133
	v_or_b32_e32 v80, 24, v85
	v_mul_lo_u32 v84, v42, s25
	v_cmp_gt_u32_e64 s[64:65], v80, v133
	v_or_b32_e32 v80, 25, v85
	v_lshl_add_u32 v135, v81, 5, v84
	s_movk_i32 s25, 0xffe8
	v_cmp_gt_u32_e64 s[66:67], v80, v133
	v_or_b32_e32 v80, 26, v85
	v_mad_i32_i24 v138, v81, s25, v135
	s_movk_i32 s25, 0xffb4
	v_mul_u32_u24_e32 v81, 0x880, v81
	v_cmp_gt_u32_e64 s[68:69], v80, v133
	v_or_b32_e32 v80, 27, v85
	v_add_lshl_u32 v139, v42, v81, 1
	v_cmp_gt_u32_e64 s[70:71], v80, v133
	v_mul_u32_u24_e32 v80, 0x50, v133
	v_sub_u32_e32 v81, s27, v32
	v_cmp_lt_u32_e64 s[42:43], v85, v133
	v_subrev_u32_e32 v149, 33, v81
	v_add_u32_e32 v151, v32, v80
	s_waitcnt vmcnt(0)
	v_lshl_or_b32 v41, v82, 16, v41
	v_mul_u32_u24_e32 v82, 0x110, v133
	v_or_b32_e32 v137, v82, v136
	v_lshl_add_u64 v[82:83], v[116:117], 2, s[40:41]
	v_lshl_add_u64 v[126:127], v[82:83], 0, v[32:33]
	v_mul_lo_u32 v82, v42, s25
	v_cmp_gt_u32_e64 s[40:41], v85, v133
	v_add_u32_e32 v150, v84, v82
	s_mov_b32 s25, 0
	s_setprio 2
	s_branch .LBB0_785
.LBB0_784:
	s_waitcnt lgkmcnt(0)
	s_barrier
	s_setprio 3
	v_add_u32_e32 v156, v137, v136
	ds_read_b128 v[80:83], v156 offset:8704
	ds_read_b128 v[84:87], v156
	ds_read_b128 v[96:99], v156 offset:32
	ds_read_b128 v[100:103], v156 offset:8736
	v_cvt_pk_bf16_f32 v184, v8, v9
	v_cvt_pk_bf16_f32 v185, v10, v11
	s_waitcnt lgkmcnt(2)
	v_mfma_f32_32x32x16_bf16 v[80:95], v[80:83], v[84:87], 0
	v_cvt_pk_bf16_f32 v186, v12, v13
	v_cvt_pk_bf16_f32 v187, v14, v15
	v_cvt_pk_bf16_f32 v188, v16, v17
	v_cvt_pk_bf16_f32 v189, v18, v19
	v_cvt_pk_bf16_f32 v190, v20, v21
	v_cvt_pk_bf16_f32 v191, v22, v23
	v_cvt_pk_bf16_f32 v196, v56, v57
	s_waitcnt lgkmcnt(0)
	v_mfma_f32_32x32x16_bf16 v[80:95], v[100:103], v[96:99], v[80:95]
	ds_read_b128 v[96:99], v156 offset:8768
	ds_read_b128 v[100:103], v156 offset:64
	ds_read_b128 v[104:107], v156 offset:8800
	ds_read_b128 v[108:111], v156 offset:96
	v_cvt_pk_bf16_f32 v197, v58, v59
	v_cvt_pk_bf16_f32 v198, v60, v61
	v_cvt_pk_bf16_f32 v199, v62, v63
	s_waitcnt lgkmcnt(2)
	v_mfma_f32_32x32x16_bf16 v[80:95], v[96:99], v[100:103], v[80:95]
	s_waitcnt lgkmcnt(0)
	v_mfma_f32_32x32x16_bf16 v[80:95], v[104:107], v[108:111], v[80:95]
	ds_read_b128 v[96:99], v156 offset:8832
	ds_read_b128 v[100:103], v156 offset:128
	ds_read_b128 v[104:107], v156 offset:8864
	ds_read_b128 v[108:111], v156 offset:160
	s_waitcnt lgkmcnt(2)
	v_mfma_f32_32x32x16_bf16 v[80:95], v[96:99], v[100:103], v[80:95]
	s_waitcnt lgkmcnt(0)
	v_mfma_f32_32x32x16_bf16 v[80:95], v[104:107], v[108:111], v[80:95]
	ds_read_b128 v[96:99], v156 offset:8896
	ds_read_b128 v[100:103], v156 offset:192
	ds_read_b128 v[104:107], v156 offset:8928
	ds_read_b128 v[108:111], v156 offset:224
	v_add_u32_e32 v156, v138, v136
	s_waitcnt lgkmcnt(2)
	v_mfma_f32_32x32x16_bf16 v[80:95], v[96:99], v[100:103], v[80:95]
	v_cvt_pk_bf16_f32 v96, v0, v1
	v_cvt_pk_bf16_f32 v97, v2, v3
	v_cvt_pk_bf16_f32 v98, v4, v5
	v_cvt_pk_bf16_f32 v99, v6, v7
	ds_read2_b64 v[100:103], v137 offset1:2
	ds_read2_b64 v[180:183], v137 offset0:4 offset1:6
	ds_read2_b64 v[192:195], v137 offset0:16 offset1:18
	s_waitcnt lgkmcnt(3)
	v_mfma_f32_32x32x16_bf16 v[80:95], v[104:107], v[108:111], v[80:95]
	s_waitcnt lgkmcnt(2)
	v_mfma_f32_32x32x16_bf16 v[96:111], v[96:99], v[100:103], 0
	s_nop 9
	v_cndmask_b32_e64 v157, 0, v81, s[42:43]
	v_cndmask_b32_e64 v160, v82, 0, s[44:45]
	v_cndmask_b32_e64 v161, v83, 0, s[46:47]
	v_cndmask_b32_e64 v92, v92, 0, s[64:65]
	s_waitcnt lgkmcnt(1)
	v_mfma_f32_32x32x16_bf16 v[96:111], v[184:187], v[180:183], v[96:111]
	ds_read2_b64 v[180:183], v137 offset0:8 offset1:10
	v_cvt_pk_bf16_f32 v184, v24, v25
	v_cvt_pk_bf16_f32 v185, v26, v27
	v_cvt_pk_bf16_f32 v186, v28, v29
	v_cvt_pk_bf16_f32 v187, v30, v31
	s_waitcnt lgkmcnt(0)
	v_mfma_f32_32x32x16_bf16 v[96:111], v[188:191], v[180:183], v[96:111]
	ds_read2_b64 v[180:183], v137 offset0:12 offset1:14
	v_cvt_pk_bf16_f32 v188, v48, v49
	v_cvt_pk_bf16_f32 v189, v50, v51
	v_cvt_pk_bf16_f32 v190, v52, v53
	v_cvt_pk_bf16_f32 v191, v54, v55
	s_waitcnt lgkmcnt(0)
	v_mfma_f32_32x32x16_bf16 v[96:111], v[184:187], v[180:183], v[96:111]
	ds_read2_b64 v[180:183], v137 offset0:20 offset1:22
	v_cvt_pk_bf16_f32 v184, v64, v65
	v_cvt_pk_bf16_f32 v185, v66, v67
	v_cvt_pk_bf16_f32 v186, v68, v69
	v_cvt_pk_bf16_f32 v187, v70, v71
	v_mfma_f32_32x32x16_bf16 v[96:111], v[188:191], v[192:195], v[96:111]
	ds_read_b128 v[188:191], v32 offset:37952
	ds_read_b128 v[192:195], v32 offset:37984
	ds_read_b128 v[200:203], v32 offset:37888
	ds_read_b128 v[204:207], v32 offset:37920
	ds_read2_b64 v[208:211], v137 offset0:24 offset1:26
	s_waitcnt lgkmcnt(4)
	v_pk_mul_f32 v[10:11], v[10:11], v[190:191]
	s_waitcnt lgkmcnt(3)
	v_pk_mul_f32 v[14:15], v[14:15], v[194:195]
	s_waitcnt lgkmcnt(1)
	v_pk_mul_f32 v[6:7], v[6:7], v[206:207]
	v_mfma_f32_32x32x16_bf16 v[96:111], v[196:199], v[180:183], v[96:111]
	ds_read_b128 v[180:183], v151 offset:17408
	v_mul_f32_e64 v2, v2, v202
	v_mul_f32_e64 v3, v3, v203
	v_mul_f32_e64 v12, v12, v192
	v_mul_f32_e64 v13, v13, v193
	v_pk_mul_f32 v[8:9], v[8:9], v[188:189]
	v_pk_mul_f32 v[4:5], v[4:5], v[204:205]
	v_pk_mul_f32 v[0:1], v[0:1], v[200:201]
	s_waitcnt lgkmcnt(1)
	v_mfma_f32_32x32x16_bf16 v[96:111], v[184:187], v[208:211], v[96:111]
	ds_read_b128 v[184:187], v156 offset:27648
	ds_read_b128 v[188:191], v151 offset:17440
	ds_read_b128 v[192:195], v156 offset:27680
	ds_read_b128 v[196:199], v32 offset:38080
	ds_read_b128 v[200:203], v32 offset:38112
	v_cvt_pk_bf16_f32 v208, v72, v73
	v_cvt_pk_bf16_f32 v209, v74, v75
	v_cndmask_b32_e64 v156, v80, 0, s[40:41]
	s_waitcnt lgkmcnt(1)
	v_pk_mul_f32 v[26:27], v[26:27], v[198:199]
	s_waitcnt lgkmcnt(0)
	v_pk_mul_f32 v[30:31], v[30:31], v[202:203]
	v_pk_mul_f32 v[28:29], v[28:29], v[200:201]
	v_mfma_f32_32x32x16_bf16 v[0:15], v[180:183], v[184:187], v[0:15]
	ds_read_b128 v[180:183], v32 offset:38048
	ds_read_b128 v[204:207], v32 offset:38016
	ds_read_b128 v[210:213], v151 offset:19968
	v_mul_f32_e64 v24, v24, v196
	v_mul_f32_e64 v25, v25, v197
	v_cndmask_b32_e64 v156, v156, v80, s[42:43]
	s_waitcnt lgkmcnt(2)
	v_pk_mul_f32 v[22:23], v[22:23], v[182:183]
	s_waitcnt lgkmcnt(1)
	v_pk_mul_f32 v[18:19], v[18:19], v[206:207]
	v_pk_mul_f32 v[20:21], v[20:21], v[180:181]
	v_pk_mul_f32 v[16:17], v[16:17], v[204:205]
	v_mfma_f32_32x32x16_bf16 v[0:15], v[188:191], v[192:195], v[0:15]
	ds_read_b128 v[180:183], v151 offset:20000
	ds_read_b128 v[188:191], v32 offset:38208
	ds_read_b128 v[196:199], v32 offset:38240
	ds_read_b128 v[200:203], v32 offset:38144
	ds_read_b128 v[204:207], v32 offset:38176
	s_waitcnt lgkmcnt(3)
	v_pk_mul_f32 v[58:59], v[58:59], v[190:191]
	s_waitcnt lgkmcnt(2)
	v_pk_mul_f32 v[62:63], v[62:63], v[198:199]
	s_waitcnt lgkmcnt(0)
	v_pk_mul_f32 v[54:55], v[54:55], v[206:207]
	v_mfma_f32_32x32x16_bf16 v[16:31], v[210:213], v[184:187], v[16:31]
	ds_read_b128 v[212:215], v151 offset:22528
	v_mul_f32_e64 v50, v50, v202
	v_mul_f32_e64 v51, v51, v203
	v_mul_f32_e64 v60, v60, v196
	v_mul_f32_e64 v61, v61, v197
	v_pk_mul_f32 v[56:57], v[56:57], v[188:189]
	v_pk_mul_f32 v[52:53], v[52:53], v[204:205]
	v_pk_mul_f32 v[48:49], v[48:49], v[200:201]
	v_cvt_pk_bf16_f32 v210, v76, v77
	v_mfma_f32_32x32x16_bf16 v[16:31], v[180:183], v[192:195], v[16:31]
	ds_read_b128 v[180:183], v151 offset:22560
	ds_read_b128 v[188:191], v32 offset:38336
	ds_read_b128 v[196:199], v32 offset:38368
	v_cvt_pk_bf16_f32 v211, v78, v79
	s_waitcnt lgkmcnt(1)
	v_pk_mul_f32 v[74:75], v[74:75], v[190:191]
	s_waitcnt lgkmcnt(0)
	v_pk_mul_f32 v[78:79], v[78:79], v[198:199]
	v_mfma_f32_32x32x16_bf16 v[48:63], v[212:215], v[184:187], v[48:63]
	ds_read2_b64 v[200:203], v137 offset0:28 offset1:30
	ds_read_b128 v[204:207], v32 offset:38272
	ds_read_b128 v[212:215], v32 offset:38304
	ds_read_b128 v[216:219], v151 offset:25088
	v_mul_f32_e64 v76, v76, v196
	v_mul_f32_e64 v77, v77, v197
	v_pk_mul_f32 v[72:73], v[72:73], v[188:189]
	s_waitcnt lgkmcnt(2)
	v_pk_mul_f32 v[66:67], v[66:67], v[206:207]
	s_waitcnt lgkmcnt(1)
	v_pk_mul_f32 v[70:71], v[70:71], v[214:215]
	v_pk_mul_f32 v[68:69], v[68:69], v[212:213]
	v_mfma_f32_32x32x16_bf16 v[48:63], v[180:183], v[192:195], v[48:63]
	v_mul_f32_e64 v64, v64, v204
	v_mul_f32_e64 v65, v65, v205
	ds_read_b128 v[180:183], v151 offset:25120
	s_waitcnt lgkmcnt(1)
	v_mfma_f32_32x32x16_bf16 v[64:79], v[216:219], v[184:187], v[64:79]
	v_cndmask_b32_e64 v184, v84, 0, s[48:49]
	v_add_u32_e32 v84, 0x6800, v138
	ds_read2_b64 v[80:83], v84 offset0:128 offset1:130
	v_cndmask_b32_e64 v185, v85, 0, s[50:51]
	v_cndmask_b32_e64 v186, v90, 0, s[60:61]
	v_cndmask_b32_e64 v187, v91, 0, s[62:63]
	v_cvt_pk_bf16_f32 v90, v184, v185
	v_mfma_f32_32x32x16_bf16 v[96:111], v[208:211], v[200:203], v[96:111]
	s_waitcnt lgkmcnt(1)
	v_mfma_f32_32x32x16_bf16 v[64:79], v[180:183], v[192:195], v[64:79]
	v_cndmask_b32_e64 v180, v86, 0, s[52:53]
	v_cndmask_b32_e64 v181, v87, 0, s[54:55]
	v_cndmask_b32_e64 v182, v88, 0, s[56:57]
	v_cndmask_b32_e64 v183, v89, 0, s[58:59]
	ds_read2_b64 v[84:87], v84 offset0:132 offset1:134
	v_cvt_pk_bf16_f32 v88, v156, v157
	v_cvt_pk_bf16_f32 v89, v160, v161
	v_cvt_pk_bf16_f32 v91, v180, v181
	s_waitcnt lgkmcnt(1)
	s_nop 0
	v_mfma_f32_32x32x16_bf16 v[96:111], v[80:83], v[88:91], v[96:111]
	v_cndmask_b32_e64 v82, v93, 0, s[66:67]
	v_cndmask_b32_e64 v83, v94, 0, s[68:69]
	v_cndmask_b32_e64 v88, v95, 0, s[70:71]
	v_cvt_pk_bf16_f32 v80, v182, v183
	v_cvt_pk_bf16_f32 v81, v186, v187
	v_cvt_pk_bf16_f32 v82, v92, v82
	v_cvt_pk_bf16_f32 v83, v83, v88
	s_waitcnt lgkmcnt(0)
	s_nop 0
	v_mfma_f32_32x32x16_bf16 v[96:111], v[84:87], v[80:83], v[96:111]
	s_setprio 2
	v_add_u32_e32 v80, s31, v133
	v_cndmask_b32_e32 v80, v148, v80, vcc
	v_add_u32_e32 v80, s97, v80
	v_ashrrev_i32_e32 v81, 31, v80
	v_lshlrev_b64 v[80:81], 11, v[80:81]
	s_add_i32 s31, s31, 32
	v_lshl_add_u64 v[80:81], v[126:127], 0, v[80:81]
	v_subrev_u32_e32 v148, 32, v148
	s_cmp_eq_u32 s30, s25
	v_subrev_u32_e32 v149, 32, v149
	s_nop 0
	global_store_dwordx4 v[80:81], v[96:99], off
	global_store_dwordx4 v[80:81], v[100:103], off offset:32
	global_store_dwordx4 v[80:81], v[104:107], off offset:64
	global_store_dwordx4 v[80:81], v[108:111], off offset:96
	s_barrier
	s_cbranch_scc1 .LBB0_789
	s_waitcnt vmcnt(4)
	v_lshl_or_b32 v113, v236, 16, v113
	v_lshl_or_b32 v34, v237, 16, v34
	v_lshl_or_b32 v115, v238, 16, v115
	v_lshl_or_b32 v35, v239, 16, v35
	v_lshl_or_b32 v134, v240, 16, v134
	v_lshl_or_b32 v36, v241, 16, v36
	v_lshl_or_b32 v140, v242, 16, v140
	v_lshl_or_b32 v37, v243, 16, v37
	v_lshl_or_b32 v38, v244, 16, v38
	v_lshl_or_b32 v152, v245, 16, v152
	v_lshl_or_b32 v39, v246, 16, v39
	v_lshl_or_b32 v153, v247, 16, v153
	v_lshl_or_b32 v40, v248, 16, v40
	v_lshl_or_b32 v154, v249, 16, v154
	v_lshl_or_b32 v155, v250, 16, v155
	v_lshl_or_b32 v41, v251, 16, v41

.LBB0_789:
	s_setprio 0
	v_readlane_b32 s52, v233, 61
	v_readlane_b32 s0, v232, 55
	v_readlane_b32 s54, v233, 63
	v_readlane_b32 s55, v232, 0
	v_readlane_b32 s1, v232, 56
	v_readlane_b32 s56, v232, 1
	v_readlane_b32 s57, v232, 2
	v_readlane_b32 s62, v232, 7
	v_readlane_b32 s63, v232, 8
	v_readlane_b32 s70, v232, 13
	v_readlane_b32 s68, v232, 15
	v_readlane_b32 s54, v232, 50
	s_and_b64 vcc, exec, s[0:1]
	v_readlane_b32 s53, v233, 62
	v_readlane_b32 s58, v232, 3
	v_readlane_b32 s59, v232, 4
	v_readlane_b32 s60, v232, 5
	v_readlane_b32 s61, v232, 6
	v_readlane_b32 s64, v232, 9
	v_readlane_b32 s65, v232, 10
	v_readlane_b32 s66, v232, 11
	v_readlane_b32 s67, v232, 12
	v_readlane_b32 s71, v232, 14
	v_readlane_b32 s69, v232, 16
	v_readlane_b32 s63, v235, 21
	s_movk_i32 s97, 0xb00
	v_readlane_b32 s62, v232, 31
	v_readlane_b32 s55, v232, 51
	v_readlane_b32 s21, v232, 52
	v_readlane_b32 s56, v232, 53
	v_readlane_b32 s57, v232, 54
	s_cbranch_vccz .LBB0_192
	v_readlane_b32 s0, v232, 57
	s_lshl_b32 s0, s0, 2
	v_readlane_b32 s24, v232, 48
	v_readlane_b32 s25, v232, 49
	s_add_u32 s0, s24, s0
	s_addc_u32 s1, s25, 0
	s_or_b64 s[0:1], s[0:1], s[2:3]
	s_lshl_b64 s[0:1], s[0:1], 18
	v_readlane_b32 s2, v234, 18
	s_add_u32 s0, s2, s0
	v_readlane_b32 s2, v234, 19
	s_addc_u32 s1, s2, s1
	v_readlane_b32 s2, v232, 58
	s_lshl_b32 s2, s2, 16
	s_add_u32 s0, s0, s2
	s_addc_u32 s1, s1, 0
	v_lshl_add_u64 v[34:35], v[116:117], 2, s[0:1]
	v_mov_b32_e32 v115, v33
	v_lshl_add_u64 v[34:35], v[34:35], 0, v[114:115]
	v_mov_b32_e32 v113, v33
	v_lshl_add_u64 v[34:35], v[34:35], 0, v[112:113]
	s_movk_i32 s0, 0x1000
	global_store_dword v[34:35], v0, off
	global_store_dword v[34:35], v1, off offset:512
	global_store_dword v[34:35], v2, off offset:1024
	global_store_dword v[34:35], v3, off offset:1536
	v_add_co_u32_e32 v0, vcc, s0, v34
	s_movk_i32 s0, 0x2000
	s_nop 0
	v_addc_co_u32_e32 v1, vcc, 0, v35, vcc
	v_add_co_u32_e32 v2, vcc, s0, v34
	s_movk_i32 s0, 0x3000
	s_nop 0
	v_addc_co_u32_e32 v3, vcc, 0, v35, vcc
	global_store_dword v[2:3], v4, off offset:-4096
	global_store_dword v[0:1], v5, off offset:512
	global_store_dword v[0:1], v6, off offset:1024
	global_store_dword v[0:1], v7, off offset:1536
	global_store_dword v[2:3], v8, off
	global_store_dword v[2:3], v9, off offset:512
	global_store_dword v[2:3], v10, off offset:1024
	global_store_dword v[2:3], v11, off offset:1536
	v_add_co_u32_e32 v0, vcc, s0, v34
	s_movk_i32 s0, 0x4000
	s_nop 0
	v_addc_co_u32_e32 v1, vcc, 0, v35, vcc
	v_add_co_u32_e32 v2, vcc, s0, v34
	s_movk_i32 s0, 0x5000
	s_nop 0
	v_addc_co_u32_e32 v3, vcc, 0, v35, vcc
	global_store_dword v[2:3], v12, off offset:-4096
	global_store_dword v[0:1], v13, off offset:512
	global_store_dword v[0:1], v14, off offset:1024
	global_store_dword v[0:1], v15, off offset:1536
	global_store_dword v[2:3], v16, off
	global_store_dword v[2:3], v17, off offset:512
	global_store_dword v[2:3], v18, off offset:1024
	global_store_dword v[2:3], v19, off offset:1536
	v_add_co_u32_e32 v0, vcc, s0, v34
	s_movk_i32 s0, 0x7000
	s_nop 0
	v_addc_co_u32_e32 v1, vcc, 0, v35, vcc
	v_add_co_u32_e32 v2, vcc, s79, v34
	s_nop 1
	v_addc_co_u32_e32 v3, vcc, 0, v35, vcc
	global_store_dword v[2:3], v20, off offset:-4096
	global_store_dword v[0:1], v21, off offset:512
	global_store_dword v[0:1], v22, off offset:1024
	global_store_dword v[0:1], v23, off offset:1536
	global_store_dword v[2:3], v24, off
	global_store_dword v[2:3], v25, off offset:512
	global_store_dword v[2:3], v26, off offset:1024
	global_store_dword v[2:3], v27, off offset:1536
	v_add_co_u32_e32 v0, vcc, s0, v34
	s_mov_b32 s0, 0x8000
	s_nop 0
	v_addc_co_u32_e32 v1, vcc, 0, v35, vcc
	v_add_co_u32_e32 v2, vcc, s0, v34
	s_mov_b32 s0, 0x9000
	s_nop 0
	v_addc_co_u32_e32 v3, vcc, 0, v35, vcc
	global_store_dword v[2:3], v28, off offset:-4096
	global_store_dword v[0:1], v29, off offset:512
	global_store_dword v[0:1], v30, off offset:1024
	global_store_dword v[0:1], v31, off offset:1536
	global_store_dword v[2:3], v48, off
	global_store_dword v[2:3], v49, off offset:512
	global_store_dword v[2:3], v50, off offset:1024
	global_store_dword v[2:3], v51, off offset:1536
	v_add_co_u32_e32 v0, vcc, s0, v34
	s_mov_b32 s0, 0xa000
	s_nop 0
	v_addc_co_u32_e32 v1, vcc, 0, v35, vcc
	v_add_co_u32_e32 v2, vcc, s0, v34
	s_mov_b32 s0, 0xb000
	s_nop 0
	v_addc_co_u32_e32 v3, vcc, 0, v35, vcc
	global_store_dword v[2:3], v52, off offset:-4096
	global_store_dword v[0:1], v53, off offset:512
	global_store_dword v[0:1], v54, off offset:1024
	global_store_dword v[0:1], v55, off offset:1536
	global_store_dword v[2:3], v56, off
	global_store_dword v[2:3], v57, off offset:512
	global_store_dword v[2:3], v58, off offset:1024
	global_store_dword v[2:3], v59, off offset:1536
	v_add_co_u32_e32 v0, vcc, s0, v34
	s_mov_b32 s0, 0xd000
	s_nop 0
	v_addc_co_u32_e32 v1, vcc, 0, v35, vcc
	v_add_co_u32_e32 v2, vcc, s35, v34
	s_nop 1
	v_addc_co_u32_e32 v3, vcc, 0, v35, vcc
	global_store_dword v[2:3], v60, off offset:-4096
	global_store_dword v[0:1], v61, off offset:512
	global_store_dword v[0:1], v62, off offset:1024
	global_store_dword v[0:1], v63, off offset:1536
	global_store_dword v[2:3], v64, off
	global_store_dword v[2:3], v65, off offset:512
	global_store_dword v[2:3], v66, off offset:1024
	global_store_dword v[2:3], v67, off offset:1536
	v_add_co_u32_e32 v0, vcc, s0, v34
	s_mov_b32 s0, 0xe000
	s_nop 0
	v_addc_co_u32_e32 v1, vcc, 0, v35, vcc
	v_add_co_u32_e32 v2, vcc, s0, v34
	s_nop 1
	v_addc_co_u32_e32 v3, vcc, 0, v35, vcc
	global_store_dword v[2:3], v68, off offset:-4096
	global_store_dword v[0:1], v69, off offset:512
	global_store_dword v[0:1], v70, off offset:1024
	global_store_dword v[0:1], v71, off offset:1536
	global_store_dword v[2:3], v72, off
	global_store_dword v[2:3], v73, off offset:512
	global_store_dword v[2:3], v74, off offset:1024
	global_store_dword v[2:3], v75, off offset:1536
	v_add_co_u32_e32 v0, vcc, 0xf000, v34
	s_nop 1
	v_addc_co_u32_e32 v1, vcc, 0, v35, vcc
	global_store_dword v[0:1], v76, off
	global_store_dword v[0:1], v77, off offset:512
	global_store_dword v[0:1], v78, off offset:1024
	global_store_dword v[0:1], v79, off offset:1536
	s_branch .LBB0_192
